# P4: packed v_pk_fma_f32 (score scale+bias between QK and PV MFMA groups) split into scalar v_fma_f32 pairs
# speedup vs baseline: 1.0090x; 1.0090x over previous
; #define LAS __attribute__((address_space(3)))
; __device__ __forceinline__ void p4_attn(const Params& p, unsigned char* lds, int bid, int nb, bool dry) {
;     ...
;       const int slotb = ch * 32 + 4 * g;
;       const u32x2 k0 = *(const LAS u32x2*)(idxs + tok * 256 + slotb), k1 = *(const LAS u32x2*)(idxs + tok * 256 + slotb + 16);
;       float lg0[4], lg1[4]; float mx = -1e30f;
;       const bool full = (ch * 32 + 32 <= nk);
;       int dd0[4], dd1[4]; int dmin = 1 << 20;
; #pragma unroll
;       for (int i = 0; i < 4; ++i) {
;         const int key0 = (int)((k0[i >> 1] >> (16 * (i & 1))) & 0xffffu), key1 = (int)((k1[i >> 1] >> (16 * (i & 1))) & 0xffffu);
;         dd0[i] = t - key0; dd1[i] = t - key1; dmin = min(dmin, min(dd0[i], dd1[i]));
;       }
;       if (__ballot(dmin < 128) == 0ull) {
;         const float bfar = biasd[128 * 32 + head];
; #pragma unroll
;         for (int i = 0; i < 4; ++i) { lg0[i] = s0[i] * SC + bfar; lg1[i] = s1[i] * SC + bfar; }
;       } else {
; #pragma unroll
;         for (int i = 0; i < 4; ++i) {
;           const int d0 = min(max(dd0[i], 0), 128), d1 = min(max(dd1[i], 0), 128);
;           lg0[i] = s0[i] * SC + biasd[d0 * 32 + head];
;           lg1[i] = s1[i] * SC + biasd[d1 * 32 + head];
;         }
;       }
.Lp4_softmax:
	s_waitcnt lgkmcnt(0)
	v_or_b32_e32 v0, s13, v148
	v_add_u32_e32 v192, s12, v163
	v_add3_u32 v192, v192, v164, v165
	v_sub_u32_sdwa v3, s14, v187 dst_sel:DWORD dst_unused:UNUSED_PAD src0_sel:DWORD src1_sel:WORD_1
	v_sub_u32_sdwa v136, s14, v184 dst_sel:DWORD dst_unused:UNUSED_PAD src0_sel:DWORD src1_sel:WORD_0
	v_sub_u32_sdwa v137, s14, v186 dst_sel:DWORD dst_unused:UNUSED_PAD src0_sel:DWORD src1_sel:WORD_0
	v_sub_u32_sdwa v134, s14, v184 dst_sel:DWORD dst_unused:UNUSED_PAD src0_sel:DWORD src1_sel:WORD_1
	v_sub_u32_sdwa v135, s14, v186 dst_sel:DWORD dst_unused:UNUSED_PAD src0_sel:DWORD src1_sel:WORD_1
	v_sub_u32_sdwa v132, s14, v185 dst_sel:DWORD dst_unused:UNUSED_PAD src0_sel:DWORD src1_sel:WORD_0
	v_sub_u32_sdwa v133, s14, v187 dst_sel:DWORD dst_unused:UNUSED_PAD src0_sel:DWORD src1_sel:WORD_0
	v_sub_u32_sdwa v2, s14, v185 dst_sel:DWORD dst_unused:UNUSED_PAD src0_sel:DWORD src1_sel:WORD_1
	v_min_i32_e32 v138, v134, v135
	v_min3_i32 v138, v136, v137, v138
	v_min_i32_e32 v139, v132, v133
	v_min_i32_e32 v193, v2, v3
	v_min3_i32 v138, v138, v139, v193
	v_cmp_gt_i32_e32 vcc, s16, v138
	s_cbranch_vccz .Lp4_far
	v_med3_i32 v136, v136, 0, v172
	v_med3_i32 v137, v137, 0, v172
	v_med3_i32 v132, v132, 0, v172
	v_med3_i32 v133, v133, 0, v172
	v_med3_i32 v2, v2, 0, v172
	v_med3_i32 v134, v134, 0, v172
	v_med3_i32 v135, v135, 0, v172
	v_med3_i32 v3, v3, 0, v172
	v_lshl_add_u32 v136, v136, 7, v169
	v_lshl_add_u32 v137, v137, 7, v169
	v_lshl_add_u32 v132, v132, 7, v169
	v_lshl_add_u32 v133, v133, 7, v169
	v_lshl_add_u32 v139, v2, 7, v169
	v_lshl_add_u32 v134, v134, 7, v169
	v_lshl_add_u32 v135, v135, 7, v169
	v_lshl_add_u32 v193, v3, 7, v169
	ds_read_b32 v2, v136
	ds_read_b32 v136, v137
	ds_read_b32 v132, v132
	ds_read_b32 v138, v133
	ds_read_b32 v133, v139
	ds_read_b32 v3, v134
	ds_read_b32 v139, v193
	ds_read_b32 v137, v135
	ds_read_b64_tr_b16 v[234:235], v192
	ds_read_b64_tr_b16 v[236:237], v192 offset:8704
	ds_read_b64_tr_b16 v[238:239], v192 offset:32
	ds_read_b64_tr_b16 v[240:241], v192 offset:8736
	ds_read_b64_tr_b16 v[242:243], v192 offset:64
	ds_read_b64_tr_b16 v[244:245], v192 offset:8768
	s_waitcnt lgkmcnt(6)
	v_fma_f32 v134, v142, s4, v132
	v_fma_f32 v135, v143, s4, v133
	v_fma_f32 v132, v140, s4, v2
	v_fma_f32 v133, v141, s4, v3
	v_fma_f32 v138, v146, s4, v138
	v_fma_f32 v139, v147, s4, v139
	v_fma_f32 v136, v144, s4, v136
	v_fma_f32 v137, v145, s4, v137
	ds_read_b64_tr_b16 v[246:247], v192 offset:96
	ds_read_b64_tr_b16 v[248:249], v192 offset:8800
	ds_read_b64_tr_b16 v[250:251], v192 offset:128
	ds_read_b64_tr_b16 v[252:253], v192 offset:8832
	ds_read_b64_tr_b16 v[188:189], v192 offset:160
	ds_read_b64_tr_b16 v[190:191], v192 offset:8864
	ds_read_b64_tr_b16 v[176:177], v192 offset:192
	ds_read_b64_tr_b16 v[178:179], v192 offset:8896
	s_branch .Lp4_lg
.Lp4_far:
	ds_read_b32 v2, v169 offset:16384
	ds_read_b64_tr_b16 v[234:235], v192
	ds_read_b64_tr_b16 v[236:237], v192 offset:8704
	ds_read_b64_tr_b16 v[238:239], v192 offset:32
	ds_read_b64_tr_b16 v[240:241], v192 offset:8736
	ds_read_b64_tr_b16 v[242:243], v192 offset:64
	ds_read_b64_tr_b16 v[244:245], v192 offset:8768
	ds_read_b64_tr_b16 v[246:247], v192 offset:96
	ds_read_b64_tr_b16 v[248:249], v192 offset:8800
	ds_read_b64_tr_b16 v[250:251], v192 offset:128
	ds_read_b64_tr_b16 v[252:253], v192 offset:8832
	ds_read_b64_tr_b16 v[188:189], v192 offset:160
	ds_read_b64_tr_b16 v[190:191], v192 offset:8864
	ds_read_b64_tr_b16 v[176:177], v192 offset:192
	ds_read_b64_tr_b16 v[178:179], v192 offset:8896
	s_waitcnt lgkmcnt(14)
	v_fma_f32 v134, v142, s4, v2
	v_fma_f32 v135, v143, s4, v2
	v_fma_f32 v132, v140, s4, v2
	v_fma_f32 v133, v141, s4, v2
	v_fma_f32 v138, v146, s4, v2
	v_fma_f32 v139, v147, s4, v2
	v_fma_f32 v136, v144, s4, v2
	v_fma_f32 v137, v145, s4, v2
